# prologue x->bf16 and p->bf16 fast path re-mapped to 8 contiguous elements per lane: 16-byte bf16 stores (half the store instructions)
# speedup vs baseline: 1.0065x; 1.0065x over previous
; __device__ __forceinline__ unsigned cvt_pk_bf16(float lo, float hi) { unsigned r; asm volatile("v_cvt_pk_bf16_f32 %0, %1, %2" : "=v"(r) : "v"(lo), "v"(hi)); return r; }
; __device__ void phase_prologue(KP P, LAS unsigned char* lds) {
;     ...
;     bf16_t* xb = (bf16_t*)(ws + OFF_XB); float* ssq = (float*)(ws + OFF_SSQ);
; #pragma unroll 8
;     for (int row = gw; row < MTOK; row += nw) { float s = 0.f;
; #pragma unroll
;         for (int i = 0; i < 4; ++i) { const int col = lane * 4 + 256 * i; const f32x4 v = __builtin_nontemporal_load((const f32x4*)(P->x + (size_t)row * 1024 + col));
;             s += v.x * v.x + v.y * v.y + v.z * v.z + v.w * v.w; u32x2 w; w.x = cvt_pk_bf16(v.x, v.y); w.y = cvt_pk_bf16(v.z, v.w); *(u32x2*)(xb + (size_t)row * 1024 + col) = w; }
; #pragma unroll
;         for (int d = 32; d >= 1; d >>= 1) s += __shfl_xor(s, d);
;         if (lane == 0) ssq[row] = s; }
.LBB0_525:
	s_or_b64 exec, exec, s[6:7]
	s_cmpk_lg_u32 s54, 0x100
	s_cbranch_scc1 .Lpro_generic
	s_load_dwordx2 s[8:9], s[36:37], 0x0
	s_load_dwordx2 s[18:19], s[36:37], 0x8
	v_and_b32_e32 v160, 63, v208
	v_lshrrev_b32_e32 v161, 6, v208
	v_lshlrev_b32_e32 v162, 5, v160
	v_lshlrev_b32_e32 v163, 4, v160
	v_mov_b32_e32 v164, 0
	v_readfirstlane_b32 s1, v161
	s_lshl_b32 s3, s2, 3
	s_add_i32 s3, s3, s1
	s_mov_b32 s4, s3
	s_mov_b32 s5, 0
	s_lshl_b64 s[10:11], s[4:5], 12
	s_lshl_b64 s[12:13], s[4:5], 11
	s_lshl_b64 s[14:15], s[4:5], 2
	s_waitcnt lgkmcnt(0)
	s_add_u32 s8, s8, s10
	s_addc_u32 s9, s9, s11
	s_add_u32 s10, s90, 0x4700000
	s_addc_u32 s11, s91, 0
	s_add_u32 s10, s10, s12
	s_addc_u32 s11, s11, s13
	s_add_u32 s12, s90, 0x8700000
	s_addc_u32 s13, s91, 0
	s_add_u32 s12, s12, s14
	s_addc_u32 s13, s13, s15
	s_add_u32 s14, s8, 0x0
	s_addc_u32 s15, s9, 0
	global_load_dwordx4 v[0:3], v162, s[14:15] nt
	global_load_dwordx4 v[4:7], v162, s[14:15] offset:16 nt
	global_load_dwordx4 v[8:11], v162, s[14:15] offset:2048 nt
	global_load_dwordx4 v[12:15], v162, s[14:15] offset:2064 nt
	s_add_u32 s14, s8, 0x800000
	s_addc_u32 s15, s9, 0
	global_load_dwordx4 v[16:19], v162, s[14:15] nt
	global_load_dwordx4 v[20:23], v162, s[14:15] offset:16 nt
	global_load_dwordx4 v[24:27], v162, s[14:15] offset:2048 nt
	global_load_dwordx4 v[28:31], v162, s[14:15] offset:2064 nt
	s_add_u32 s14, s8, 0x1000000
	s_addc_u32 s15, s9, 0
	global_load_dwordx4 v[32:35], v162, s[14:15] nt
	global_load_dwordx4 v[36:39], v162, s[14:15] offset:16 nt
	global_load_dwordx4 v[40:43], v162, s[14:15] offset:2048 nt
	global_load_dwordx4 v[44:47], v162, s[14:15] offset:2064 nt
	s_add_u32 s14, s8, 0x1800000
	s_addc_u32 s15, s9, 0
	global_load_dwordx4 v[48:51], v162, s[14:15] nt
	global_load_dwordx4 v[52:55], v162, s[14:15] offset:16 nt
	global_load_dwordx4 v[56:59], v162, s[14:15] offset:2048 nt
	global_load_dwordx4 v[60:63], v162, s[14:15] offset:2064 nt
	s_add_u32 s14, s8, 0x2000000
	s_addc_u32 s15, s9, 0
	global_load_dwordx4 v[64:67], v162, s[14:15] nt
	global_load_dwordx4 v[68:71], v162, s[14:15] offset:16 nt
	global_load_dwordx4 v[72:75], v162, s[14:15] offset:2048 nt
	global_load_dwordx4 v[76:79], v162, s[14:15] offset:2064 nt
	s_add_u32 s14, s8, 0x2800000
	s_addc_u32 s15, s9, 0
	global_load_dwordx4 v[80:83], v162, s[14:15] nt
	global_load_dwordx4 v[84:87], v162, s[14:15] offset:16 nt
	global_load_dwordx4 v[88:91], v162, s[14:15] offset:2048 nt
	global_load_dwordx4 v[92:95], v162, s[14:15] offset:2064 nt
	s_add_u32 s14, s8, 0x3000000
	s_addc_u32 s15, s9, 0
	global_load_dwordx4 v[96:99], v162, s[14:15] nt
	global_load_dwordx4 v[100:103], v162, s[14:15] offset:16 nt
	global_load_dwordx4 v[104:107], v162, s[14:15] offset:2048 nt
	global_load_dwordx4 v[108:111], v162, s[14:15] offset:2064 nt
	s_add_u32 s14, s8, 0x3800000
	s_addc_u32 s15, s9, 0
	global_load_dwordx4 v[112:115], v162, s[14:15] nt
	global_load_dwordx4 v[116:119], v162, s[14:15] offset:16 nt
	global_load_dwordx4 v[120:123], v162, s[14:15] offset:2048 nt
	global_load_dwordx4 v[124:127], v162, s[14:15] offset:2064 nt
	s_waitcnt vmcnt(28)
	s_add_u32 s16, s10, 0x0
	s_addc_u32 s17, s11, 0
	v_mul_f32_e32 v128, v1, v1
	v_fmac_f32_e32 v128, v0, v0
	v_fmac_f32_e32 v128, v2, v2
	v_fmac_f32_e32 v128, v3, v3
	v_mul_f32_e32 v129, v5, v5
	v_fmac_f32_e32 v129, v4, v4
	v_fmac_f32_e32 v129, v6, v6
	v_fmac_f32_e32 v129, v7, v7
	v_mul_f32_e32 v130, v9, v9
	v_fmac_f32_e32 v130, v8, v8
	v_fmac_f32_e32 v130, v10, v10
	v_fmac_f32_e32 v130, v11, v11
	v_mul_f32_e32 v131, v13, v13
	v_fmac_f32_e32 v131, v12, v12
	v_fmac_f32_e32 v131, v14, v14
	v_fmac_f32_e32 v131, v15, v15
	v_add_f32_e32 v128, v128, v129
	v_add_f32_e32 v128, v128, v130
	v_add_f32_e32 v128, v128, v131
	v_cvt_pk_bf16_f32 v132, v0, v1
	v_cvt_pk_bf16_f32 v133, v2, v3
	v_cvt_pk_bf16_f32 v134, v4, v5
	v_cvt_pk_bf16_f32 v135, v6, v7
	v_cvt_pk_bf16_f32 v136, v8, v9
	v_cvt_pk_bf16_f32 v137, v10, v11
	v_cvt_pk_bf16_f32 v138, v12, v13
	v_cvt_pk_bf16_f32 v139, v14, v15
	global_store_dwordx4 v163, v[132:135], s[16:17]
	global_store_dwordx4 v163, v[136:139], s[16:17] offset:1024
	v_add_f32_dpp v128, v128, v128 quad_perm:[1,0,3,2] row_mask:0xf bank_mask:0xf
	s_nop 1
	v_add_f32_dpp v128, v128, v128 quad_perm:[2,3,0,1] row_mask:0xf bank_mask:0xf
	s_nop 1
	v_add_f32_dpp v128, v128, v128 row_half_mirror row_mask:0xf bank_mask:0xf
	s_nop 1
	v_add_f32_dpp v128, v128, v128 row_mirror row_mask:0xf bank_mask:0xf
	s_nop 1
	v_add_f32_dpp v128, v128, v128 row_bcast:15 row_mask:0xa bank_mask:0xf
	s_nop 1
	v_add_f32_dpp v128, v128, v128 row_bcast:31 row_mask:0xc bank_mask:0xf
	s_nop 1
	v_readlane_b32 s1, v128, 63
	s_add_u32 s14, s12, 0x0
	s_addc_u32 s15, s13, 0
	s_mov_b64 exec, 1
	v_mov_b32_e32 v129, s1
	global_store_dword v164, v129, s[14:15]
	s_mov_b64 exec, -1
	s_add_u32 s14, s8, 0x4000000
	s_addc_u32 s15, s9, 0
	global_load_dwordx4 v[0:3], v162, s[14:15] nt
	global_load_dwordx4 v[4:7], v162, s[14:15] offset:16 nt
	global_load_dwordx4 v[8:11], v162, s[14:15] offset:2048 nt
	global_load_dwordx4 v[12:15], v162, s[14:15] offset:2064 nt
	s_waitcnt vmcnt(31)
; __device__ __forceinline__ unsigned cvt_pk_bf16(float lo, float hi) { unsigned r; asm volatile("v_cvt_pk_bf16_f32 %0, %1, %2" : "=v"(r) : "v"(lo), "v"(hi)); return r; }
; __device__ void phase_prologue(KP P, LAS unsigned char* lds) {
;     ...
;     bf16_t* xb = (bf16_t*)(ws + OFF_XB); float* ssq = (float*)(ws + OFF_SSQ);
; #pragma unroll 8
;     for (int row = gw; row < MTOK; row += nw) { float s = 0.f;
; #pragma unroll
;         for (int i = 0; i < 4; ++i) { const int col = lane * 4 + 256 * i; const f32x4 v = __builtin_nontemporal_load((const f32x4*)(P->x + (size_t)row * 1024 + col));
;             s += v.x * v.x + v.y * v.y + v.z * v.z + v.w * v.w; u32x2 w; w.x = cvt_pk_bf16(v.x, v.y); w.y = cvt_pk_bf16(v.z, v.w); *(u32x2*)(xb + (size_t)row * 1024 + col) = w; }
; #pragma unroll
;         for (int d = 32; d >= 1; d >>= 1) s += __shfl_xor(s, d);
;         if (lane == 0) ssq[row] = s; }
	s_add_u32 s16, s10, 0x400000
	s_addc_u32 s17, s11, 0
	v_mul_f32_e32 v128, v17, v17
	v_fmac_f32_e32 v128, v16, v16
	v_fmac_f32_e32 v128, v18, v18
	v_fmac_f32_e32 v128, v19, v19
	v_mul_f32_e32 v129, v21, v21
	v_fmac_f32_e32 v129, v20, v20
	v_fmac_f32_e32 v129, v22, v22
	v_fmac_f32_e32 v129, v23, v23
	v_mul_f32_e32 v130, v25, v25
	v_fmac_f32_e32 v130, v24, v24
	v_fmac_f32_e32 v130, v26, v26
	v_fmac_f32_e32 v130, v27, v27
	v_mul_f32_e32 v131, v29, v29
	v_fmac_f32_e32 v131, v28, v28
	v_fmac_f32_e32 v131, v30, v30
	v_fmac_f32_e32 v131, v31, v31
	v_add_f32_e32 v128, v128, v129
	v_add_f32_e32 v128, v128, v130
	v_add_f32_e32 v128, v128, v131
	v_cvt_pk_bf16_f32 v132, v16, v17
	v_cvt_pk_bf16_f32 v133, v18, v19
	v_cvt_pk_bf16_f32 v134, v20, v21
	v_cvt_pk_bf16_f32 v135, v22, v23
	v_cvt_pk_bf16_f32 v136, v24, v25
	v_cvt_pk_bf16_f32 v137, v26, v27
	v_cvt_pk_bf16_f32 v138, v28, v29
	v_cvt_pk_bf16_f32 v139, v30, v31
	global_store_dwordx4 v163, v[132:135], s[16:17]
	global_store_dwordx4 v163, v[136:139], s[16:17] offset:1024
	v_add_f32_dpp v128, v128, v128 quad_perm:[1,0,3,2] row_mask:0xf bank_mask:0xf
	s_nop 1
	v_add_f32_dpp v128, v128, v128 quad_perm:[2,3,0,1] row_mask:0xf bank_mask:0xf
	s_nop 1
	v_add_f32_dpp v128, v128, v128 row_half_mirror row_mask:0xf bank_mask:0xf
	s_nop 1
	v_add_f32_dpp v128, v128, v128 row_mirror row_mask:0xf bank_mask:0xf
	s_nop 1
	v_add_f32_dpp v128, v128, v128 row_bcast:15 row_mask:0xa bank_mask:0xf
	s_nop 1
	v_add_f32_dpp v128, v128, v128 row_bcast:31 row_mask:0xc bank_mask:0xf
	s_nop 1
	v_readlane_b32 s1, v128, 63
	s_add_u32 s14, s12, 0x2000
	s_addc_u32 s15, s13, 0
	s_mov_b64 exec, 1
	v_mov_b32_e32 v129, s1
	global_store_dword v164, v129, s[14:15]
	s_mov_b64 exec, -1
	s_add_u32 s14, s8, 0x4800000
	s_addc_u32 s15, s9, 0
	global_load_dwordx4 v[16:19], v162, s[14:15] nt
	global_load_dwordx4 v[20:23], v162, s[14:15] offset:16 nt
	global_load_dwordx4 v[24:27], v162, s[14:15] offset:2048 nt
	global_load_dwordx4 v[28:31], v162, s[14:15] offset:2064 nt
	s_waitcnt vmcnt(34)
	s_add_u32 s16, s10, 0x800000
	s_addc_u32 s17, s11, 0
	v_mul_f32_e32 v128, v33, v33
	v_fmac_f32_e32 v128, v32, v32
	v_fmac_f32_e32 v128, v34, v34
	v_fmac_f32_e32 v128, v35, v35
	v_mul_f32_e32 v129, v37, v37
	v_fmac_f32_e32 v129, v36, v36
	v_fmac_f32_e32 v129, v38, v38
	v_fmac_f32_e32 v129, v39, v39
	v_mul_f32_e32 v130, v41, v41
	v_fmac_f32_e32 v130, v40, v40
	v_fmac_f32_e32 v130, v42, v42
	v_fmac_f32_e32 v130, v43, v43
	v_mul_f32_e32 v131, v45, v45
	v_fmac_f32_e32 v131, v44, v44
	v_fmac_f32_e32 v131, v46, v46
	v_fmac_f32_e32 v131, v47, v47
	v_add_f32_e32 v128, v128, v129
	v_add_f32_e32 v128, v128, v130
	v_add_f32_e32 v128, v128, v131
	v_cvt_pk_bf16_f32 v132, v32, v33
	v_cvt_pk_bf16_f32 v133, v34, v35
	v_cvt_pk_bf16_f32 v134, v36, v37
	v_cvt_pk_bf16_f32 v135, v38, v39
	v_cvt_pk_bf16_f32 v136, v40, v41
	v_cvt_pk_bf16_f32 v137, v42, v43
	v_cvt_pk_bf16_f32 v138, v44, v45
	v_cvt_pk_bf16_f32 v139, v46, v47
	global_store_dwordx4 v163, v[132:135], s[16:17]
	global_store_dwordx4 v163, v[136:139], s[16:17] offset:1024
	v_add_f32_dpp v128, v128, v128 quad_perm:[1,0,3,2] row_mask:0xf bank_mask:0xf
	s_nop 1
	v_add_f32_dpp v128, v128, v128 quad_perm:[2,3,0,1] row_mask:0xf bank_mask:0xf
	s_nop 1
	v_add_f32_dpp v128, v128, v128 row_half_mirror row_mask:0xf bank_mask:0xf
	s_nop 1
	v_add_f32_dpp v128, v128, v128 row_mirror row_mask:0xf bank_mask:0xf
	s_nop 1
	v_add_f32_dpp v128, v128, v128 row_bcast:15 row_mask:0xa bank_mask:0xf
	s_nop 1
	v_add_f32_dpp v128, v128, v128 row_bcast:31 row_mask:0xc bank_mask:0xf
	s_nop 1
	v_readlane_b32 s1, v128, 63
	s_add_u32 s14, s12, 0x4000
	s_addc_u32 s15, s13, 0
	s_mov_b64 exec, 1
	v_mov_b32_e32 v129, s1
	global_store_dword v164, v129, s[14:15]
	s_mov_b64 exec, -1
	s_add_u32 s14, s8, 0x5000000
	s_addc_u32 s15, s9, 0
	global_load_dwordx4 v[32:35], v162, s[14:15] nt
	global_load_dwordx4 v[36:39], v162, s[14:15] offset:16 nt
	global_load_dwordx4 v[40:43], v162, s[14:15] offset:2048 nt
	global_load_dwordx4 v[44:47], v162, s[14:15] offset:2064 nt
	s_waitcnt vmcnt(37)
	s_add_u32 s16, s10, 0xc00000
	s_addc_u32 s17, s11, 0
	v_mul_f32_e32 v128, v49, v49
	v_fmac_f32_e32 v128, v48, v48
	v_fmac_f32_e32 v128, v50, v50
	v_fmac_f32_e32 v128, v51, v51
	v_mul_f32_e32 v129, v53, v53
	v_fmac_f32_e32 v129, v52, v52
	v_fmac_f32_e32 v129, v54, v54
	v_fmac_f32_e32 v129, v55, v55
	v_mul_f32_e32 v130, v57, v57
	v_fmac_f32_e32 v130, v56, v56
	v_fmac_f32_e32 v130, v58, v58
	v_fmac_f32_e32 v130, v59, v59
	v_mul_f32_e32 v131, v61, v61
	v_fmac_f32_e32 v131, v60, v60
	v_fmac_f32_e32 v131, v62, v62
	v_fmac_f32_e32 v131, v63, v63
	v_add_f32_e32 v128, v128, v129
	v_add_f32_e32 v128, v128, v130
	v_add_f32_e32 v128, v128, v131
	v_cvt_pk_bf16_f32 v132, v48, v49
	v_cvt_pk_bf16_f32 v133, v50, v51
	v_cvt_pk_bf16_f32 v134, v52, v53
	v_cvt_pk_bf16_f32 v135, v54, v55
	v_cvt_pk_bf16_f32 v136, v56, v57
	v_cvt_pk_bf16_f32 v137, v58, v59
	v_cvt_pk_bf16_f32 v138, v60, v61
	v_cvt_pk_bf16_f32 v139, v62, v63
	global_store_dwordx4 v163, v[132:135], s[16:17]
	global_store_dwordx4 v163, v[136:139], s[16:17] offset:1024
	v_add_f32_dpp v128, v128, v128 quad_perm:[1,0,3,2] row_mask:0xf bank_mask:0xf
	s_nop 1
	v_add_f32_dpp v128, v128, v128 quad_perm:[2,3,0,1] row_mask:0xf bank_mask:0xf
	s_nop 1
	v_add_f32_dpp v128, v128, v128 row_half_mirror row_mask:0xf bank_mask:0xf
	s_nop 1
	v_add_f32_dpp v128, v128, v128 row_mirror row_mask:0xf bank_mask:0xf
	s_nop 1
	v_add_f32_dpp v128, v128, v128 row_bcast:15 row_mask:0xa bank_mask:0xf
	s_nop 1
	v_add_f32_dpp v128, v128, v128 row_bcast:31 row_mask:0xc bank_mask:0xf
	s_nop 1
	v_readlane_b32 s1, v128, 63
	s_add_u32 s14, s12, 0x6000
	s_addc_u32 s15, s13, 0
	s_mov_b64 exec, 1
	v_mov_b32_e32 v129, s1
	global_store_dword v164, v129, s[14:15]
	s_mov_b64 exec, -1
	s_add_u32 s14, s8, 0x5800000
	s_addc_u32 s15, s9, 0
	global_load_dwordx4 v[48:51], v162, s[14:15] nt
	global_load_dwordx4 v[52:55], v162, s[14:15] offset:16 nt
	global_load_dwordx4 v[56:59], v162, s[14:15] offset:2048 nt
	global_load_dwordx4 v[60:63], v162, s[14:15] offset:2064 nt
	s_waitcnt vmcnt(40)
; __device__ __forceinline__ unsigned cvt_pk_bf16(float lo, float hi) { unsigned r; asm volatile("v_cvt_pk_bf16_f32 %0, %1, %2" : "=v"(r) : "v"(lo), "v"(hi)); return r; }
; __device__ void phase_prologue(KP P, LAS unsigned char* lds) {
;     ...
;     for (int row = gw; row < MTOK; row += nw) { float s = 0.f;
; #pragma unroll
;         for (int i = 0; i < 4; ++i) { const int col = lane * 4 + 256 * i; const f32x4 v = __builtin_nontemporal_load((const f32x4*)(P->x + (size_t)row * 1024 + col));
;             s += v.x * v.x + v.y * v.y + v.z * v.z + v.w * v.w; u32x2 w; w.x = cvt_pk_bf16(v.x, v.y); w.y = cvt_pk_bf16(v.z, v.w); *(u32x2*)(xb + (size_t)row * 1024 + col) = w; }
; #pragma unroll
;         for (int d = 32; d >= 1; d >>= 1) s += __shfl_xor(s, d);
;         if (lane == 0) ssq[row] = s; }
	s_add_u32 s16, s10, 0x1000000
	s_addc_u32 s17, s11, 0
	v_mul_f32_e32 v128, v65, v65
	v_fmac_f32_e32 v128, v64, v64
	v_fmac_f32_e32 v128, v66, v66
	v_fmac_f32_e32 v128, v67, v67
	v_mul_f32_e32 v129, v69, v69
	v_fmac_f32_e32 v129, v68, v68
	v_fmac_f32_e32 v129, v70, v70
	v_fmac_f32_e32 v129, v71, v71
	v_mul_f32_e32 v130, v73, v73
	v_fmac_f32_e32 v130, v72, v72
	v_fmac_f32_e32 v130, v74, v74
	v_fmac_f32_e32 v130, v75, v75
	v_mul_f32_e32 v131, v77, v77
	v_fmac_f32_e32 v131, v76, v76
	v_fmac_f32_e32 v131, v78, v78
	v_fmac_f32_e32 v131, v79, v79
	v_add_f32_e32 v128, v128, v129
	v_add_f32_e32 v128, v128, v130
	v_add_f32_e32 v128, v128, v131
	v_cvt_pk_bf16_f32 v132, v64, v65
	v_cvt_pk_bf16_f32 v133, v66, v67
	v_cvt_pk_bf16_f32 v134, v68, v69
	v_cvt_pk_bf16_f32 v135, v70, v71
	v_cvt_pk_bf16_f32 v136, v72, v73
	v_cvt_pk_bf16_f32 v137, v74, v75
	v_cvt_pk_bf16_f32 v138, v76, v77
	v_cvt_pk_bf16_f32 v139, v78, v79
	global_store_dwordx4 v163, v[132:135], s[16:17]
	global_store_dwordx4 v163, v[136:139], s[16:17] offset:1024
	v_add_f32_dpp v128, v128, v128 quad_perm:[1,0,3,2] row_mask:0xf bank_mask:0xf
	s_nop 1
	v_add_f32_dpp v128, v128, v128 quad_perm:[2,3,0,1] row_mask:0xf bank_mask:0xf
	s_nop 1
	v_add_f32_dpp v128, v128, v128 row_half_mirror row_mask:0xf bank_mask:0xf
	s_nop 1
	v_add_f32_dpp v128, v128, v128 row_mirror row_mask:0xf bank_mask:0xf
	s_nop 1
	v_add_f32_dpp v128, v128, v128 row_bcast:15 row_mask:0xa bank_mask:0xf
	s_nop 1
	v_add_f32_dpp v128, v128, v128 row_bcast:31 row_mask:0xc bank_mask:0xf
	s_nop 1
	v_readlane_b32 s1, v128, 63
	s_add_u32 s14, s12, 0x8000
	s_addc_u32 s15, s13, 0
	s_mov_b64 exec, 1
	v_mov_b32_e32 v129, s1
	global_store_dword v164, v129, s[14:15]
	s_mov_b64 exec, -1
	s_add_u32 s14, s8, 0x6000000
	s_addc_u32 s15, s9, 0
	global_load_dwordx4 v[64:67], v162, s[14:15] nt
	global_load_dwordx4 v[68:71], v162, s[14:15] offset:16 nt
	global_load_dwordx4 v[72:75], v162, s[14:15] offset:2048 nt
	global_load_dwordx4 v[76:79], v162, s[14:15] offset:2064 nt
	s_waitcnt vmcnt(43)
	s_add_u32 s16, s10, 0x1400000
	s_addc_u32 s17, s11, 0
	v_mul_f32_e32 v128, v81, v81
	v_fmac_f32_e32 v128, v80, v80
	v_fmac_f32_e32 v128, v82, v82
	v_fmac_f32_e32 v128, v83, v83
	v_mul_f32_e32 v129, v85, v85
	v_fmac_f32_e32 v129, v84, v84
	v_fmac_f32_e32 v129, v86, v86
	v_fmac_f32_e32 v129, v87, v87
	v_mul_f32_e32 v130, v89, v89
	v_fmac_f32_e32 v130, v88, v88
	v_fmac_f32_e32 v130, v90, v90
	v_fmac_f32_e32 v130, v91, v91
	v_mul_f32_e32 v131, v93, v93
	v_fmac_f32_e32 v131, v92, v92
	v_fmac_f32_e32 v131, v94, v94
	v_fmac_f32_e32 v131, v95, v95
	v_add_f32_e32 v128, v128, v129
	v_add_f32_e32 v128, v128, v130
	v_add_f32_e32 v128, v128, v131
	v_cvt_pk_bf16_f32 v132, v80, v81
	v_cvt_pk_bf16_f32 v133, v82, v83
	v_cvt_pk_bf16_f32 v134, v84, v85
	v_cvt_pk_bf16_f32 v135, v86, v87
	v_cvt_pk_bf16_f32 v136, v88, v89
	v_cvt_pk_bf16_f32 v137, v90, v91
	v_cvt_pk_bf16_f32 v138, v92, v93
	v_cvt_pk_bf16_f32 v139, v94, v95
	global_store_dwordx4 v163, v[132:135], s[16:17]
	global_store_dwordx4 v163, v[136:139], s[16:17] offset:1024
	v_add_f32_dpp v128, v128, v128 quad_perm:[1,0,3,2] row_mask:0xf bank_mask:0xf
	s_nop 1
	v_add_f32_dpp v128, v128, v128 quad_perm:[2,3,0,1] row_mask:0xf bank_mask:0xf
	s_nop 1
	v_add_f32_dpp v128, v128, v128 row_half_mirror row_mask:0xf bank_mask:0xf
	s_nop 1
	v_add_f32_dpp v128, v128, v128 row_mirror row_mask:0xf bank_mask:0xf
	s_nop 1
	v_add_f32_dpp v128, v128, v128 row_bcast:15 row_mask:0xa bank_mask:0xf
	s_nop 1
	v_add_f32_dpp v128, v128, v128 row_bcast:31 row_mask:0xc bank_mask:0xf
	s_nop 1
	v_readlane_b32 s1, v128, 63
	s_add_u32 s14, s12, 0xa000
	s_addc_u32 s15, s13, 0
	s_mov_b64 exec, 1
	v_mov_b32_e32 v129, s1
	global_store_dword v164, v129, s[14:15]
	s_mov_b64 exec, -1
	s_add_u32 s14, s8, 0x6800000
	s_addc_u32 s15, s9, 0
	global_load_dwordx4 v[80:83], v162, s[14:15] nt
	global_load_dwordx4 v[84:87], v162, s[14:15] offset:16 nt
	global_load_dwordx4 v[88:91], v162, s[14:15] offset:2048 nt
	global_load_dwordx4 v[92:95], v162, s[14:15] offset:2064 nt
	s_waitcnt vmcnt(46)
	s_add_u32 s16, s10, 0x1800000
	s_addc_u32 s17, s11, 0
	v_mul_f32_e32 v128, v97, v97
	v_fmac_f32_e32 v128, v96, v96
	v_fmac_f32_e32 v128, v98, v98
	v_fmac_f32_e32 v128, v99, v99
	v_mul_f32_e32 v129, v101, v101
	v_fmac_f32_e32 v129, v100, v100
	v_fmac_f32_e32 v129, v102, v102
	v_fmac_f32_e32 v129, v103, v103
	v_mul_f32_e32 v130, v105, v105
	v_fmac_f32_e32 v130, v104, v104
	v_fmac_f32_e32 v130, v106, v106
	v_fmac_f32_e32 v130, v107, v107
	v_mul_f32_e32 v131, v109, v109
	v_fmac_f32_e32 v131, v108, v108
	v_fmac_f32_e32 v131, v110, v110
	v_fmac_f32_e32 v131, v111, v111
	v_add_f32_e32 v128, v128, v129
	v_add_f32_e32 v128, v128, v130
	v_add_f32_e32 v128, v128, v131
	v_cvt_pk_bf16_f32 v132, v96, v97
	v_cvt_pk_bf16_f32 v133, v98, v99
	v_cvt_pk_bf16_f32 v134, v100, v101
	v_cvt_pk_bf16_f32 v135, v102, v103
	v_cvt_pk_bf16_f32 v136, v104, v105
	v_cvt_pk_bf16_f32 v137, v106, v107
	v_cvt_pk_bf16_f32 v138, v108, v109
	v_cvt_pk_bf16_f32 v139, v110, v111
	global_store_dwordx4 v163, v[132:135], s[16:17]
	global_store_dwordx4 v163, v[136:139], s[16:17] offset:1024
	v_add_f32_dpp v128, v128, v128 quad_perm:[1,0,3,2] row_mask:0xf bank_mask:0xf
	s_nop 1
	v_add_f32_dpp v128, v128, v128 quad_perm:[2,3,0,1] row_mask:0xf bank_mask:0xf
	s_nop 1
	v_add_f32_dpp v128, v128, v128 row_half_mirror row_mask:0xf bank_mask:0xf
	s_nop 1
	v_add_f32_dpp v128, v128, v128 row_mirror row_mask:0xf bank_mask:0xf
	s_nop 1
	v_add_f32_dpp v128, v128, v128 row_bcast:15 row_mask:0xa bank_mask:0xf
	s_nop 1
	v_add_f32_dpp v128, v128, v128 row_bcast:31 row_mask:0xc bank_mask:0xf
	s_nop 1
	v_readlane_b32 s1, v128, 63
	s_add_u32 s14, s12, 0xc000
	s_addc_u32 s15, s13, 0
	s_mov_b64 exec, 1
	v_mov_b32_e32 v129, s1
	global_store_dword v164, v129, s[14:15]
	s_mov_b64 exec, -1
	s_add_u32 s14, s8, 0x7000000
	s_addc_u32 s15, s9, 0
	global_load_dwordx4 v[96:99], v162, s[14:15] nt
	global_load_dwordx4 v[100:103], v162, s[14:15] offset:16 nt
	global_load_dwordx4 v[104:107], v162, s[14:15] offset:2048 nt
	global_load_dwordx4 v[108:111], v162, s[14:15] offset:2064 nt
	s_waitcnt vmcnt(49)
; __device__ __forceinline__ unsigned cvt_pk_bf16(float lo, float hi) { unsigned r; asm volatile("v_cvt_pk_bf16_f32 %0, %1, %2" : "=v"(r) : "v"(lo), "v"(hi)); return r; }
; __device__ void phase_prologue(KP P, LAS unsigned char* lds) {
;     ...
;     for (int row = gw; row < MTOK; row += nw) { float s = 0.f;
; #pragma unroll
;         for (int i = 0; i < 4; ++i) { const int col = lane * 4 + 256 * i; const f32x4 v = __builtin_nontemporal_load((const f32x4*)(P->x + (size_t)row * 1024 + col));
;             s += v.x * v.x + v.y * v.y + v.z * v.z + v.w * v.w; u32x2 w; w.x = cvt_pk_bf16(v.x, v.y); w.y = cvt_pk_bf16(v.z, v.w); *(u32x2*)(xb + (size_t)row * 1024 + col) = w; }
; #pragma unroll
;         for (int d = 32; d >= 1; d >>= 1) s += __shfl_xor(s, d);
;         if (lane == 0) ssq[row] = s; }
	s_add_u32 s16, s10, 0x1c00000
	s_addc_u32 s17, s11, 0
	v_mul_f32_e32 v128, v113, v113
	v_fmac_f32_e32 v128, v112, v112
	v_fmac_f32_e32 v128, v114, v114
	v_fmac_f32_e32 v128, v115, v115
	v_mul_f32_e32 v129, v117, v117
	v_fmac_f32_e32 v129, v116, v116
	v_fmac_f32_e32 v129, v118, v118
	v_fmac_f32_e32 v129, v119, v119
	v_mul_f32_e32 v130, v121, v121
	v_fmac_f32_e32 v130, v120, v120
	v_fmac_f32_e32 v130, v122, v122
	v_fmac_f32_e32 v130, v123, v123
	v_mul_f32_e32 v131, v125, v125
	v_fmac_f32_e32 v131, v124, v124
	v_fmac_f32_e32 v131, v126, v126
	v_fmac_f32_e32 v131, v127, v127
	v_add_f32_e32 v128, v128, v129
	v_add_f32_e32 v128, v128, v130
	v_add_f32_e32 v128, v128, v131
	v_cvt_pk_bf16_f32 v132, v112, v113
	v_cvt_pk_bf16_f32 v133, v114, v115
	v_cvt_pk_bf16_f32 v134, v116, v117
	v_cvt_pk_bf16_f32 v135, v118, v119
	v_cvt_pk_bf16_f32 v136, v120, v121
	v_cvt_pk_bf16_f32 v137, v122, v123
	v_cvt_pk_bf16_f32 v138, v124, v125
	v_cvt_pk_bf16_f32 v139, v126, v127
	global_store_dwordx4 v163, v[132:135], s[16:17]
	global_store_dwordx4 v163, v[136:139], s[16:17] offset:1024
	v_add_f32_dpp v128, v128, v128 quad_perm:[1,0,3,2] row_mask:0xf bank_mask:0xf
	s_nop 1
	v_add_f32_dpp v128, v128, v128 quad_perm:[2,3,0,1] row_mask:0xf bank_mask:0xf
	s_nop 1
	v_add_f32_dpp v128, v128, v128 row_half_mirror row_mask:0xf bank_mask:0xf
	s_nop 1
	v_add_f32_dpp v128, v128, v128 row_mirror row_mask:0xf bank_mask:0xf
	s_nop 1
	v_add_f32_dpp v128, v128, v128 row_bcast:15 row_mask:0xa bank_mask:0xf
	s_nop 1
	v_add_f32_dpp v128, v128, v128 row_bcast:31 row_mask:0xc bank_mask:0xf
	s_nop 1
	v_readlane_b32 s1, v128, 63
	s_add_u32 s14, s12, 0xe000
	s_addc_u32 s15, s13, 0
	s_mov_b64 exec, 1
	v_mov_b32_e32 v129, s1
	global_store_dword v164, v129, s[14:15]
	s_mov_b64 exec, -1
	s_add_u32 s14, s8, 0x7800000
	s_addc_u32 s15, s9, 0
	global_load_dwordx4 v[112:115], v162, s[14:15] nt
	global_load_dwordx4 v[116:119], v162, s[14:15] offset:16 nt
	global_load_dwordx4 v[120:123], v162, s[14:15] offset:2048 nt
	global_load_dwordx4 v[124:127], v162, s[14:15] offset:2064 nt
	s_waitcnt vmcnt(49)
	s_add_u32 s16, s10, 0x2000000
	s_addc_u32 s17, s11, 0
	v_mul_f32_e32 v128, v1, v1
	v_fmac_f32_e32 v128, v0, v0
	v_fmac_f32_e32 v128, v2, v2
	v_fmac_f32_e32 v128, v3, v3
	v_mul_f32_e32 v129, v5, v5
	v_fmac_f32_e32 v129, v4, v4
	v_fmac_f32_e32 v129, v6, v6
	v_fmac_f32_e32 v129, v7, v7
	v_mul_f32_e32 v130, v9, v9
	v_fmac_f32_e32 v130, v8, v8
	v_fmac_f32_e32 v130, v10, v10
	v_fmac_f32_e32 v130, v11, v11
	v_mul_f32_e32 v131, v13, v13
	v_fmac_f32_e32 v131, v12, v12
	v_fmac_f32_e32 v131, v14, v14
	v_fmac_f32_e32 v131, v15, v15
	v_add_f32_e32 v128, v128, v129
	v_add_f32_e32 v128, v128, v130
	v_add_f32_e32 v128, v128, v131
	v_cvt_pk_bf16_f32 v132, v0, v1
	v_cvt_pk_bf16_f32 v133, v2, v3
	v_cvt_pk_bf16_f32 v134, v4, v5
	v_cvt_pk_bf16_f32 v135, v6, v7
	v_cvt_pk_bf16_f32 v136, v8, v9
	v_cvt_pk_bf16_f32 v137, v10, v11
	v_cvt_pk_bf16_f32 v138, v12, v13
	v_cvt_pk_bf16_f32 v139, v14, v15
	global_store_dwordx4 v163, v[132:135], s[16:17]
	global_store_dwordx4 v163, v[136:139], s[16:17] offset:1024
	v_add_f32_dpp v128, v128, v128 quad_perm:[1,0,3,2] row_mask:0xf bank_mask:0xf
	s_nop 1
	v_add_f32_dpp v128, v128, v128 quad_perm:[2,3,0,1] row_mask:0xf bank_mask:0xf
	s_nop 1
	v_add_f32_dpp v128, v128, v128 row_half_mirror row_mask:0xf bank_mask:0xf
	s_nop 1
	v_add_f32_dpp v128, v128, v128 row_mirror row_mask:0xf bank_mask:0xf
	s_nop 1
	v_add_f32_dpp v128, v128, v128 row_bcast:15 row_mask:0xa bank_mask:0xf
	s_nop 1
	v_add_f32_dpp v128, v128, v128 row_bcast:31 row_mask:0xc bank_mask:0xf
	s_nop 1
	v_readlane_b32 s1, v128, 63
	s_add_u32 s14, s12, 0x10000
	s_addc_u32 s15, s13, 0
	s_mov_b64 exec, 1
	v_mov_b32_e32 v129, s1
	global_store_dword v164, v129, s[14:15]
	s_mov_b64 exec, -1
	s_waitcnt vmcnt(45)
	s_add_u32 s16, s10, 0x2400000
	s_addc_u32 s17, s11, 0
	v_mul_f32_e32 v128, v17, v17
	v_fmac_f32_e32 v128, v16, v16
	v_fmac_f32_e32 v128, v18, v18
	v_fmac_f32_e32 v128, v19, v19
	v_mul_f32_e32 v129, v21, v21
	v_fmac_f32_e32 v129, v20, v20
	v_fmac_f32_e32 v129, v22, v22
	v_fmac_f32_e32 v129, v23, v23
	v_mul_f32_e32 v130, v25, v25
	v_fmac_f32_e32 v130, v24, v24
	v_fmac_f32_e32 v130, v26, v26
	v_fmac_f32_e32 v130, v27, v27
	v_mul_f32_e32 v131, v29, v29
	v_fmac_f32_e32 v131, v28, v28
	v_fmac_f32_e32 v131, v30, v30
	v_fmac_f32_e32 v131, v31, v31
	v_add_f32_e32 v128, v128, v129
	v_add_f32_e32 v128, v128, v130
	v_add_f32_e32 v128, v128, v131
	v_cvt_pk_bf16_f32 v132, v16, v17
	v_cvt_pk_bf16_f32 v133, v18, v19
	v_cvt_pk_bf16_f32 v134, v20, v21
	v_cvt_pk_bf16_f32 v135, v22, v23
	v_cvt_pk_bf16_f32 v136, v24, v25
	v_cvt_pk_bf16_f32 v137, v26, v27
	v_cvt_pk_bf16_f32 v138, v28, v29
	v_cvt_pk_bf16_f32 v139, v30, v31
	global_store_dwordx4 v163, v[132:135], s[16:17]
	global_store_dwordx4 v163, v[136:139], s[16:17] offset:1024
	v_add_f32_dpp v128, v128, v128 quad_perm:[1,0,3,2] row_mask:0xf bank_mask:0xf
	s_nop 1
	v_add_f32_dpp v128, v128, v128 quad_perm:[2,3,0,1] row_mask:0xf bank_mask:0xf
	s_nop 1
	v_add_f32_dpp v128, v128, v128 row_half_mirror row_mask:0xf bank_mask:0xf
	s_nop 1
	v_add_f32_dpp v128, v128, v128 row_mirror row_mask:0xf bank_mask:0xf
	s_nop 1
	v_add_f32_dpp v128, v128, v128 row_bcast:15 row_mask:0xa bank_mask:0xf
	s_nop 1
	v_add_f32_dpp v128, v128, v128 row_bcast:31 row_mask:0xc bank_mask:0xf
	s_nop 1
	v_readlane_b32 s1, v128, 63
	s_add_u32 s14, s12, 0x12000
	s_addc_u32 s15, s13, 0
	s_mov_b64 exec, 1
	v_mov_b32_e32 v129, s1
	global_store_dword v164, v129, s[14:15]
	s_mov_b64 exec, -1
	s_waitcnt vmcnt(41)
; __device__ __forceinline__ unsigned cvt_pk_bf16(float lo, float hi) { unsigned r; asm volatile("v_cvt_pk_bf16_f32 %0, %1, %2" : "=v"(r) : "v"(lo), "v"(hi)); return r; }
; __device__ void phase_prologue(KP P, LAS unsigned char* lds) {
;     ...
;     for (int row = gw; row < MTOK; row += nw) { float s = 0.f;
; #pragma unroll
;         for (int i = 0; i < 4; ++i) { const int col = lane * 4 + 256 * i; const f32x4 v = __builtin_nontemporal_load((const f32x4*)(P->x + (size_t)row * 1024 + col));
;             s += v.x * v.x + v.y * v.y + v.z * v.z + v.w * v.w; u32x2 w; w.x = cvt_pk_bf16(v.x, v.y); w.y = cvt_pk_bf16(v.z, v.w); *(u32x2*)(xb + (size_t)row * 1024 + col) = w; }
; #pragma unroll
;         for (int d = 32; d >= 1; d >>= 1) s += __shfl_xor(s, d);
;         if (lane == 0) ssq[row] = s; }
	s_add_u32 s16, s10, 0x2800000
	s_addc_u32 s17, s11, 0
	v_mul_f32_e32 v128, v33, v33
	v_fmac_f32_e32 v128, v32, v32
	v_fmac_f32_e32 v128, v34, v34
	v_fmac_f32_e32 v128, v35, v35
	v_mul_f32_e32 v129, v37, v37
	v_fmac_f32_e32 v129, v36, v36
	v_fmac_f32_e32 v129, v38, v38
	v_fmac_f32_e32 v129, v39, v39
	v_mul_f32_e32 v130, v41, v41
	v_fmac_f32_e32 v130, v40, v40
	v_fmac_f32_e32 v130, v42, v42
	v_fmac_f32_e32 v130, v43, v43
	v_mul_f32_e32 v131, v45, v45
	v_fmac_f32_e32 v131, v44, v44
	v_fmac_f32_e32 v131, v46, v46
	v_fmac_f32_e32 v131, v47, v47
	v_add_f32_e32 v128, v128, v129
	v_add_f32_e32 v128, v128, v130
	v_add_f32_e32 v128, v128, v131
	v_cvt_pk_bf16_f32 v132, v32, v33
	v_cvt_pk_bf16_f32 v133, v34, v35
	v_cvt_pk_bf16_f32 v134, v36, v37
	v_cvt_pk_bf16_f32 v135, v38, v39
	v_cvt_pk_bf16_f32 v136, v40, v41
	v_cvt_pk_bf16_f32 v137, v42, v43
	v_cvt_pk_bf16_f32 v138, v44, v45
	v_cvt_pk_bf16_f32 v139, v46, v47
	global_store_dwordx4 v163, v[132:135], s[16:17]
	global_store_dwordx4 v163, v[136:139], s[16:17] offset:1024
	v_add_f32_dpp v128, v128, v128 quad_perm:[1,0,3,2] row_mask:0xf bank_mask:0xf
	s_nop 1
	v_add_f32_dpp v128, v128, v128 quad_perm:[2,3,0,1] row_mask:0xf bank_mask:0xf
	s_nop 1
	v_add_f32_dpp v128, v128, v128 row_half_mirror row_mask:0xf bank_mask:0xf
	s_nop 1
	v_add_f32_dpp v128, v128, v128 row_mirror row_mask:0xf bank_mask:0xf
	s_nop 1
	v_add_f32_dpp v128, v128, v128 row_bcast:15 row_mask:0xa bank_mask:0xf
	s_nop 1
	v_add_f32_dpp v128, v128, v128 row_bcast:31 row_mask:0xc bank_mask:0xf
	s_nop 1
	v_readlane_b32 s1, v128, 63
	s_add_u32 s14, s12, 0x14000
	s_addc_u32 s15, s13, 0
	s_mov_b64 exec, 1
	v_mov_b32_e32 v129, s1
	global_store_dword v164, v129, s[14:15]
	s_mov_b64 exec, -1
	s_waitcnt vmcnt(37)
	s_add_u32 s16, s10, 0x2c00000
	s_addc_u32 s17, s11, 0
	v_mul_f32_e32 v128, v49, v49
	v_fmac_f32_e32 v128, v48, v48
	v_fmac_f32_e32 v128, v50, v50
	v_fmac_f32_e32 v128, v51, v51
	v_mul_f32_e32 v129, v53, v53
	v_fmac_f32_e32 v129, v52, v52
	v_fmac_f32_e32 v129, v54, v54
	v_fmac_f32_e32 v129, v55, v55
	v_mul_f32_e32 v130, v57, v57
	v_fmac_f32_e32 v130, v56, v56
	v_fmac_f32_e32 v130, v58, v58
	v_fmac_f32_e32 v130, v59, v59
	v_mul_f32_e32 v131, v61, v61
	v_fmac_f32_e32 v131, v60, v60
	v_fmac_f32_e32 v131, v62, v62
	v_fmac_f32_e32 v131, v63, v63
	v_add_f32_e32 v128, v128, v129
	v_add_f32_e32 v128, v128, v130
	v_add_f32_e32 v128, v128, v131
	v_cvt_pk_bf16_f32 v132, v48, v49
	v_cvt_pk_bf16_f32 v133, v50, v51
	v_cvt_pk_bf16_f32 v134, v52, v53
	v_cvt_pk_bf16_f32 v135, v54, v55
	v_cvt_pk_bf16_f32 v136, v56, v57
	v_cvt_pk_bf16_f32 v137, v58, v59
	v_cvt_pk_bf16_f32 v138, v60, v61
	v_cvt_pk_bf16_f32 v139, v62, v63
	global_store_dwordx4 v163, v[132:135], s[16:17]
	global_store_dwordx4 v163, v[136:139], s[16:17] offset:1024
	v_add_f32_dpp v128, v128, v128 quad_perm:[1,0,3,2] row_mask:0xf bank_mask:0xf
	s_nop 1
	v_add_f32_dpp v128, v128, v128 quad_perm:[2,3,0,1] row_mask:0xf bank_mask:0xf
	s_nop 1
	v_add_f32_dpp v128, v128, v128 row_half_mirror row_mask:0xf bank_mask:0xf
	s_nop 1
	v_add_f32_dpp v128, v128, v128 row_mirror row_mask:0xf bank_mask:0xf
	s_nop 1
	v_add_f32_dpp v128, v128, v128 row_bcast:15 row_mask:0xa bank_mask:0xf
	s_nop 1
	v_add_f32_dpp v128, v128, v128 row_bcast:31 row_mask:0xc bank_mask:0xf
	s_nop 1
	v_readlane_b32 s1, v128, 63
	s_add_u32 s14, s12, 0x16000
	s_addc_u32 s15, s13, 0
	s_mov_b64 exec, 1
	v_mov_b32_e32 v129, s1
	global_store_dword v164, v129, s[14:15]
	s_mov_b64 exec, -1
	s_waitcnt vmcnt(33)
	s_add_u32 s16, s10, 0x3000000
	s_addc_u32 s17, s11, 0
	v_mul_f32_e32 v128, v65, v65
	v_fmac_f32_e32 v128, v64, v64
	v_fmac_f32_e32 v128, v66, v66
	v_fmac_f32_e32 v128, v67, v67
	v_mul_f32_e32 v129, v69, v69
	v_fmac_f32_e32 v129, v68, v68
	v_fmac_f32_e32 v129, v70, v70
	v_fmac_f32_e32 v129, v71, v71
	v_mul_f32_e32 v130, v73, v73
	v_fmac_f32_e32 v130, v72, v72
	v_fmac_f32_e32 v130, v74, v74
	v_fmac_f32_e32 v130, v75, v75
	v_mul_f32_e32 v131, v77, v77
	v_fmac_f32_e32 v131, v76, v76
	v_fmac_f32_e32 v131, v78, v78
	v_fmac_f32_e32 v131, v79, v79
	v_add_f32_e32 v128, v128, v129
	v_add_f32_e32 v128, v128, v130
	v_add_f32_e32 v128, v128, v131
	v_cvt_pk_bf16_f32 v132, v64, v65
	v_cvt_pk_bf16_f32 v133, v66, v67
	v_cvt_pk_bf16_f32 v134, v68, v69
	v_cvt_pk_bf16_f32 v135, v70, v71
	v_cvt_pk_bf16_f32 v136, v72, v73
	v_cvt_pk_bf16_f32 v137, v74, v75
	v_cvt_pk_bf16_f32 v138, v76, v77
	v_cvt_pk_bf16_f32 v139, v78, v79
	global_store_dwordx4 v163, v[132:135], s[16:17]
	global_store_dwordx4 v163, v[136:139], s[16:17] offset:1024
	v_add_f32_dpp v128, v128, v128 quad_perm:[1,0,3,2] row_mask:0xf bank_mask:0xf
	s_nop 1
	v_add_f32_dpp v128, v128, v128 quad_perm:[2,3,0,1] row_mask:0xf bank_mask:0xf
	s_nop 1
	v_add_f32_dpp v128, v128, v128 row_half_mirror row_mask:0xf bank_mask:0xf
	s_nop 1
	v_add_f32_dpp v128, v128, v128 row_mirror row_mask:0xf bank_mask:0xf
	s_nop 1
	v_add_f32_dpp v128, v128, v128 row_bcast:15 row_mask:0xa bank_mask:0xf
	s_nop 1
	v_add_f32_dpp v128, v128, v128 row_bcast:31 row_mask:0xc bank_mask:0xf
	s_nop 1
	v_readlane_b32 s1, v128, 63
	s_add_u32 s14, s12, 0x18000
	s_addc_u32 s15, s13, 0
	s_mov_b64 exec, 1
	v_mov_b32_e32 v129, s1
	global_store_dword v164, v129, s[14:15]
	s_mov_b64 exec, -1
	s_waitcnt vmcnt(29)
; __device__ __forceinline__ unsigned cvt_pk_bf16(float lo, float hi) { unsigned r; asm volatile("v_cvt_pk_bf16_f32 %0, %1, %2" : "=v"(r) : "v"(lo), "v"(hi)); return r; }
; __device__ void phase_prologue(KP P, LAS unsigned char* lds) {
;     ...
;     for (int row = gw; row < MTOK; row += nw) { float s = 0.f;
; #pragma unroll
;         for (int i = 0; i < 4; ++i) { const int col = lane * 4 + 256 * i; const f32x4 v = __builtin_nontemporal_load((const f32x4*)(P->x + (size_t)row * 1024 + col));
;             s += v.x * v.x + v.y * v.y + v.z * v.z + v.w * v.w; u32x2 w; w.x = cvt_pk_bf16(v.x, v.y); w.y = cvt_pk_bf16(v.z, v.w); *(u32x2*)(xb + (size_t)row * 1024 + col) = w; }
; #pragma unroll
;         for (int d = 32; d >= 1; d >>= 1) s += __shfl_xor(s, d);
;         if (lane == 0) ssq[row] = s; }
;     ...
;     for (size_t i = (size_t)blockIdx.x * 512 + tid; i < (size_t)2 * MTOK * 256 / 4; i += (size_t)nw * 64) {
;         const f32x4 v = __builtin_nontemporal_load((const f32x4*)(P->p + i * 4)); u32x2 w; w.x = cvt_pk_bf16(v.x, v.y); w.y = cvt_pk_bf16(v.z, v.w); *(u32x2*)(pb + i * 4) = w; }
	s_add_u32 s16, s10, 0x3400000
	s_addc_u32 s17, s11, 0
	v_mul_f32_e32 v128, v81, v81
	v_fmac_f32_e32 v128, v80, v80
	v_fmac_f32_e32 v128, v82, v82
	v_fmac_f32_e32 v128, v83, v83
	v_mul_f32_e32 v129, v85, v85
	v_fmac_f32_e32 v129, v84, v84
	v_fmac_f32_e32 v129, v86, v86
	v_fmac_f32_e32 v129, v87, v87
	v_mul_f32_e32 v130, v89, v89
	v_fmac_f32_e32 v130, v88, v88
	v_fmac_f32_e32 v130, v90, v90
	v_fmac_f32_e32 v130, v91, v91
	v_mul_f32_e32 v131, v93, v93
	v_fmac_f32_e32 v131, v92, v92
	v_fmac_f32_e32 v131, v94, v94
	v_fmac_f32_e32 v131, v95, v95
	v_add_f32_e32 v128, v128, v129
	v_add_f32_e32 v128, v128, v130
	v_add_f32_e32 v128, v128, v131
	v_cvt_pk_bf16_f32 v132, v80, v81
	v_cvt_pk_bf16_f32 v133, v82, v83
	v_cvt_pk_bf16_f32 v134, v84, v85
	v_cvt_pk_bf16_f32 v135, v86, v87
	v_cvt_pk_bf16_f32 v136, v88, v89
	v_cvt_pk_bf16_f32 v137, v90, v91
	v_cvt_pk_bf16_f32 v138, v92, v93
	v_cvt_pk_bf16_f32 v139, v94, v95
	global_store_dwordx4 v163, v[132:135], s[16:17]
	global_store_dwordx4 v163, v[136:139], s[16:17] offset:1024
	v_add_f32_dpp v128, v128, v128 quad_perm:[1,0,3,2] row_mask:0xf bank_mask:0xf
	s_nop 1
	v_add_f32_dpp v128, v128, v128 quad_perm:[2,3,0,1] row_mask:0xf bank_mask:0xf
	s_nop 1
	v_add_f32_dpp v128, v128, v128 row_half_mirror row_mask:0xf bank_mask:0xf
	s_nop 1
	v_add_f32_dpp v128, v128, v128 row_mirror row_mask:0xf bank_mask:0xf
	s_nop 1
	v_add_f32_dpp v128, v128, v128 row_bcast:15 row_mask:0xa bank_mask:0xf
	s_nop 1
	v_add_f32_dpp v128, v128, v128 row_bcast:31 row_mask:0xc bank_mask:0xf
	s_nop 1
	v_readlane_b32 s1, v128, 63
	s_add_u32 s14, s12, 0x1a000
	s_addc_u32 s15, s13, 0
	s_mov_b64 exec, 1
	v_mov_b32_e32 v129, s1
	global_store_dword v164, v129, s[14:15]
	s_mov_b64 exec, -1
	s_waitcnt vmcnt(25)
	s_add_u32 s16, s10, 0x3800000
	s_addc_u32 s17, s11, 0
	v_mul_f32_e32 v128, v97, v97
	v_fmac_f32_e32 v128, v96, v96
	v_fmac_f32_e32 v128, v98, v98
	v_fmac_f32_e32 v128, v99, v99
	v_mul_f32_e32 v129, v101, v101
	v_fmac_f32_e32 v129, v100, v100
	v_fmac_f32_e32 v129, v102, v102
	v_fmac_f32_e32 v129, v103, v103
	v_mul_f32_e32 v130, v105, v105
	v_fmac_f32_e32 v130, v104, v104
	v_fmac_f32_e32 v130, v106, v106
	v_fmac_f32_e32 v130, v107, v107
	v_mul_f32_e32 v131, v109, v109
	v_fmac_f32_e32 v131, v108, v108
	v_fmac_f32_e32 v131, v110, v110
	v_fmac_f32_e32 v131, v111, v111
	v_add_f32_e32 v128, v128, v129
	v_add_f32_e32 v128, v128, v130
	v_add_f32_e32 v128, v128, v131
	v_cvt_pk_bf16_f32 v132, v96, v97
	v_cvt_pk_bf16_f32 v133, v98, v99
	v_cvt_pk_bf16_f32 v134, v100, v101
	v_cvt_pk_bf16_f32 v135, v102, v103
	v_cvt_pk_bf16_f32 v136, v104, v105
	v_cvt_pk_bf16_f32 v137, v106, v107
	v_cvt_pk_bf16_f32 v138, v108, v109
	v_cvt_pk_bf16_f32 v139, v110, v111
	global_store_dwordx4 v163, v[132:135], s[16:17]
	global_store_dwordx4 v163, v[136:139], s[16:17] offset:1024
	v_add_f32_dpp v128, v128, v128 quad_perm:[1,0,3,2] row_mask:0xf bank_mask:0xf
	s_nop 1
	v_add_f32_dpp v128, v128, v128 quad_perm:[2,3,0,1] row_mask:0xf bank_mask:0xf
	s_nop 1
	v_add_f32_dpp v128, v128, v128 row_half_mirror row_mask:0xf bank_mask:0xf
	s_nop 1
	v_add_f32_dpp v128, v128, v128 row_mirror row_mask:0xf bank_mask:0xf
	s_nop 1
	v_add_f32_dpp v128, v128, v128 row_bcast:15 row_mask:0xa bank_mask:0xf
	s_nop 1
	v_add_f32_dpp v128, v128, v128 row_bcast:31 row_mask:0xc bank_mask:0xf
	s_nop 1
	v_readlane_b32 s1, v128, 63
	s_add_u32 s14, s12, 0x1c000
	s_addc_u32 s15, s13, 0
	s_mov_b64 exec, 1
	v_mov_b32_e32 v129, s1
	global_store_dword v164, v129, s[14:15]
	s_mov_b64 exec, -1
	s_waitcnt vmcnt(21)
	s_add_u32 s16, s10, 0x3c00000
	s_addc_u32 s17, s11, 0
	v_mul_f32_e32 v128, v113, v113
	v_fmac_f32_e32 v128, v112, v112
	v_fmac_f32_e32 v128, v114, v114
	v_fmac_f32_e32 v128, v115, v115
	v_mul_f32_e32 v129, v117, v117
	v_fmac_f32_e32 v129, v116, v116
	v_fmac_f32_e32 v129, v118, v118
	v_fmac_f32_e32 v129, v119, v119
	v_mul_f32_e32 v130, v121, v121
	v_fmac_f32_e32 v130, v120, v120
	v_fmac_f32_e32 v130, v122, v122
	v_fmac_f32_e32 v130, v123, v123
	v_mul_f32_e32 v131, v125, v125
	v_fmac_f32_e32 v131, v124, v124
	v_fmac_f32_e32 v131, v126, v126
	v_fmac_f32_e32 v131, v127, v127
	v_add_f32_e32 v128, v128, v129
	v_add_f32_e32 v128, v128, v130
	v_add_f32_e32 v128, v128, v131
	v_cvt_pk_bf16_f32 v132, v112, v113
	v_cvt_pk_bf16_f32 v133, v114, v115
	v_cvt_pk_bf16_f32 v134, v116, v117
	v_cvt_pk_bf16_f32 v135, v118, v119
	v_cvt_pk_bf16_f32 v136, v120, v121
	v_cvt_pk_bf16_f32 v137, v122, v123
	v_cvt_pk_bf16_f32 v138, v124, v125
	v_cvt_pk_bf16_f32 v139, v126, v127
	global_store_dwordx4 v163, v[132:135], s[16:17]
	global_store_dwordx4 v163, v[136:139], s[16:17] offset:1024
	v_add_f32_dpp v128, v128, v128 quad_perm:[1,0,3,2] row_mask:0xf bank_mask:0xf
	s_nop 1
	v_add_f32_dpp v128, v128, v128 quad_perm:[2,3,0,1] row_mask:0xf bank_mask:0xf
	s_nop 1
	v_add_f32_dpp v128, v128, v128 row_half_mirror row_mask:0xf bank_mask:0xf
	s_nop 1
	v_add_f32_dpp v128, v128, v128 row_mirror row_mask:0xf bank_mask:0xf
	s_nop 1
	v_add_f32_dpp v128, v128, v128 row_bcast:15 row_mask:0xa bank_mask:0xf
	s_nop 1
	v_add_f32_dpp v128, v128, v128 row_bcast:31 row_mask:0xc bank_mask:0xf
	s_nop 1
	v_readlane_b32 s1, v128, 63
	s_add_u32 s14, s12, 0x1e000
	s_addc_u32 s15, s13, 0
	s_mov_b64 exec, 1
	v_mov_b32_e32 v129, s1
	global_store_dword v164, v129, s[14:15]
	s_mov_b64 exec, -1
	v_lshl_add_u32 v160, s2, 9, v208
	v_lshlrev_b32_e32 v161, 5, v160
	v_lshlrev_b32_e32 v160, 4, v160
	s_add_u32 s10, s90, 0x2700000
	s_addc_u32 s11, s91, 0
	s_add_u32 s14, s18, 0x0
	s_addc_u32 s15, s19, 0
	global_load_dwordx4 v[0:3], v161, s[14:15] nt
	global_load_dwordx4 v[4:7], v161, s[14:15] offset:16 nt
	s_add_u32 s14, s18, 0x400000
	s_addc_u32 s15, s19, 0
; __device__ __forceinline__ unsigned cvt_pk_bf16(float lo, float hi) { unsigned r; asm volatile("v_cvt_pk_bf16_f32 %0, %1, %2" : "=v"(r) : "v"(lo), "v"(hi)); return r; }
; __device__ void phase_prologue(KP P, LAS unsigned char* lds) {
;     ...
;     for (size_t i = (size_t)blockIdx.x * 512 + tid; i < (size_t)2 * MTOK * 256 / 4; i += (size_t)nw * 64) {
;         const f32x4 v = __builtin_nontemporal_load((const f32x4*)(P->p + i * 4)); u32x2 w; w.x = cvt_pk_bf16(v.x, v.y); w.y = cvt_pk_bf16(v.z, v.w); *(u32x2*)(pb + i * 4) = w; }
	global_load_dwordx4 v[8:11], v161, s[14:15] nt
	global_load_dwordx4 v[12:15], v161, s[14:15] offset:16 nt
	s_add_u32 s14, s18, 0x800000
	s_addc_u32 s15, s19, 0
	global_load_dwordx4 v[16:19], v161, s[14:15] nt
	global_load_dwordx4 v[20:23], v161, s[14:15] offset:16 nt
	s_add_u32 s14, s18, 0xc00000
	s_addc_u32 s15, s19, 0
	global_load_dwordx4 v[24:27], v161, s[14:15] nt
	global_load_dwordx4 v[28:31], v161, s[14:15] offset:16 nt
	s_add_u32 s14, s18, 0x1000000
	s_addc_u32 s15, s19, 0
	global_load_dwordx4 v[32:35], v161, s[14:15] nt
	global_load_dwordx4 v[36:39], v161, s[14:15] offset:16 nt
	s_add_u32 s14, s18, 0x1400000
	s_addc_u32 s15, s19, 0
	global_load_dwordx4 v[40:43], v161, s[14:15] nt
	global_load_dwordx4 v[44:47], v161, s[14:15] offset:16 nt
	s_add_u32 s14, s18, 0x1800000
	s_addc_u32 s15, s19, 0
	global_load_dwordx4 v[48:51], v161, s[14:15] nt
	global_load_dwordx4 v[52:55], v161, s[14:15] offset:16 nt
	s_add_u32 s14, s18, 0x1c00000
	s_addc_u32 s15, s19, 0
	global_load_dwordx4 v[56:59], v161, s[14:15] nt
	global_load_dwordx4 v[60:63], v161, s[14:15] offset:16 nt
	s_add_u32 s14, s18, 0x2000000
	s_addc_u32 s15, s19, 0
	global_load_dwordx4 v[64:67], v161, s[14:15] nt
	global_load_dwordx4 v[68:71], v161, s[14:15] offset:16 nt
	s_add_u32 s14, s18, 0x2400000
	s_addc_u32 s15, s19, 0
	global_load_dwordx4 v[72:75], v161, s[14:15] nt
	global_load_dwordx4 v[76:79], v161, s[14:15] offset:16 nt
	s_add_u32 s14, s18, 0x2800000
	s_addc_u32 s15, s19, 0
	global_load_dwordx4 v[80:83], v161, s[14:15] nt
	global_load_dwordx4 v[84:87], v161, s[14:15] offset:16 nt
	s_add_u32 s14, s18, 0x2c00000
	s_addc_u32 s15, s19, 0
	global_load_dwordx4 v[88:91], v161, s[14:15] nt
	global_load_dwordx4 v[92:95], v161, s[14:15] offset:16 nt
	s_add_u32 s14, s18, 0x3000000
	s_addc_u32 s15, s19, 0
	global_load_dwordx4 v[96:99], v161, s[14:15] nt
	global_load_dwordx4 v[100:103], v161, s[14:15] offset:16 nt
	s_add_u32 s14, s18, 0x3400000
	s_addc_u32 s15, s19, 0
	global_load_dwordx4 v[104:107], v161, s[14:15] nt
	global_load_dwordx4 v[108:111], v161, s[14:15] offset:16 nt
	s_add_u32 s14, s18, 0x3800000
	s_addc_u32 s15, s19, 0
	global_load_dwordx4 v[112:115], v161, s[14:15] nt
	global_load_dwordx4 v[116:119], v161, s[14:15] offset:16 nt
	s_add_u32 s14, s18, 0x3c00000
	s_addc_u32 s15, s19, 0
	global_load_dwordx4 v[120:123], v161, s[14:15] nt
	global_load_dwordx4 v[124:127], v161, s[14:15] offset:16 nt
	s_waitcnt vmcnt(16)
	v_cvt_pk_bf16_f32 v0, v0, v1
	v_cvt_pk_bf16_f32 v1, v2, v3
	v_cvt_pk_bf16_f32 v2, v4, v5
	v_cvt_pk_bf16_f32 v3, v6, v7
	s_add_u32 s14, s10, 0x0
	s_addc_u32 s15, s11, 0
	global_store_dwordx4 v160, v[0:3], s[14:15]
	v_cvt_pk_bf16_f32 v8, v8, v9
	v_cvt_pk_bf16_f32 v9, v10, v11
	v_cvt_pk_bf16_f32 v10, v12, v13
	v_cvt_pk_bf16_f32 v11, v14, v15
	s_add_u32 s14, s10, 0x200000
	s_addc_u32 s15, s11, 0
	global_store_dwordx4 v160, v[8:11], s[14:15]
	v_cvt_pk_bf16_f32 v16, v16, v17
	v_cvt_pk_bf16_f32 v17, v18, v19
	v_cvt_pk_bf16_f32 v18, v20, v21
	v_cvt_pk_bf16_f32 v19, v22, v23
	s_add_u32 s14, s10, 0x400000
	s_addc_u32 s15, s11, 0
	global_store_dwordx4 v160, v[16:19], s[14:15]
	v_cvt_pk_bf16_f32 v24, v24, v25
	v_cvt_pk_bf16_f32 v25, v26, v27
	v_cvt_pk_bf16_f32 v26, v28, v29
	v_cvt_pk_bf16_f32 v27, v30, v31
	s_add_u32 s14, s10, 0x600000
	s_addc_u32 s15, s11, 0
	global_store_dwordx4 v160, v[24:27], s[14:15]
	v_cvt_pk_bf16_f32 v32, v32, v33
	v_cvt_pk_bf16_f32 v33, v34, v35
	v_cvt_pk_bf16_f32 v34, v36, v37
	v_cvt_pk_bf16_f32 v35, v38, v39
	s_add_u32 s14, s10, 0x800000
	s_addc_u32 s15, s11, 0
	global_store_dwordx4 v160, v[32:35], s[14:15]
	v_cvt_pk_bf16_f32 v40, v40, v41
	v_cvt_pk_bf16_f32 v41, v42, v43
	v_cvt_pk_bf16_f32 v42, v44, v45
	v_cvt_pk_bf16_f32 v43, v46, v47
	s_add_u32 s14, s10, 0xa00000
	s_addc_u32 s15, s11, 0
	global_store_dwordx4 v160, v[40:43], s[14:15]
	v_cvt_pk_bf16_f32 v48, v48, v49
	v_cvt_pk_bf16_f32 v49, v50, v51
	v_cvt_pk_bf16_f32 v50, v52, v53
	v_cvt_pk_bf16_f32 v51, v54, v55
	s_add_u32 s14, s10, 0xc00000
	s_addc_u32 s15, s11, 0
	global_store_dwordx4 v160, v[48:51], s[14:15]
	v_cvt_pk_bf16_f32 v56, v56, v57
	v_cvt_pk_bf16_f32 v57, v58, v59
	v_cvt_pk_bf16_f32 v58, v60, v61
	v_cvt_pk_bf16_f32 v59, v62, v63
	s_add_u32 s14, s10, 0xe00000
	s_addc_u32 s15, s11, 0
	global_store_dwordx4 v160, v[56:59], s[14:15]
	s_waitcnt vmcnt(8)
	v_cvt_pk_bf16_f32 v64, v64, v65
	v_cvt_pk_bf16_f32 v65, v66, v67
	v_cvt_pk_bf16_f32 v66, v68, v69
	v_cvt_pk_bf16_f32 v67, v70, v71
	s_add_u32 s14, s10, 0x1000000
	s_addc_u32 s15, s11, 0
	global_store_dwordx4 v160, v[64:67], s[14:15]
	v_cvt_pk_bf16_f32 v72, v72, v73
	v_cvt_pk_bf16_f32 v73, v74, v75
	v_cvt_pk_bf16_f32 v74, v76, v77
	v_cvt_pk_bf16_f32 v75, v78, v79
	s_add_u32 s14, s10, 0x1200000
	s_addc_u32 s15, s11, 0
	global_store_dwordx4 v160, v[72:75], s[14:15]
	v_cvt_pk_bf16_f32 v80, v80, v81
	v_cvt_pk_bf16_f32 v81, v82, v83
	v_cvt_pk_bf16_f32 v82, v84, v85
	v_cvt_pk_bf16_f32 v83, v86, v87
	s_add_u32 s14, s10, 0x1400000
	s_addc_u32 s15, s11, 0
	global_store_dwordx4 v160, v[80:83], s[14:15]
	v_cvt_pk_bf16_f32 v88, v88, v89
	v_cvt_pk_bf16_f32 v89, v90, v91
	v_cvt_pk_bf16_f32 v90, v92, v93
	v_cvt_pk_bf16_f32 v91, v94, v95
	s_add_u32 s14, s10, 0x1600000
	s_addc_u32 s15, s11, 0
	global_store_dwordx4 v160, v[88:91], s[14:15]
	v_cvt_pk_bf16_f32 v96, v96, v97
	v_cvt_pk_bf16_f32 v97, v98, v99
	v_cvt_pk_bf16_f32 v98, v100, v101
	v_cvt_pk_bf16_f32 v99, v102, v103
	s_add_u32 s14, s10, 0x1800000
	s_addc_u32 s15, s11, 0
	global_store_dwordx4 v160, v[96:99], s[14:15]
	v_cvt_pk_bf16_f32 v104, v104, v105
	v_cvt_pk_bf16_f32 v105, v106, v107
	v_cvt_pk_bf16_f32 v106, v108, v109
	v_cvt_pk_bf16_f32 v107, v110, v111
	s_add_u32 s14, s10, 0x1a00000
	s_addc_u32 s15, s11, 0
	global_store_dwordx4 v160, v[104:107], s[14:15]
	v_cvt_pk_bf16_f32 v112, v112, v113
	v_cvt_pk_bf16_f32 v113, v114, v115
	v_cvt_pk_bf16_f32 v114, v116, v117
	v_cvt_pk_bf16_f32 v115, v118, v119
	s_add_u32 s14, s10, 0x1c00000
	s_addc_u32 s15, s11, 0
	global_store_dwordx4 v160, v[112:115], s[14:15]
	v_cvt_pk_bf16_f32 v120, v120, v121
	v_cvt_pk_bf16_f32 v121, v122, v123
	v_cvt_pk_bf16_f32 v122, v124, v125
	v_cvt_pk_bf16_f32 v123, v126, v127
	s_add_u32 s14, s10, 0x1e00000
	s_addc_u32 s15, s11, 0
	global_store_dwordx4 v160, v[120:123], s[14:15]
	s_branch .LBB0_534
